# KIND2 unit prologue: first K/V tiles requested before the bias-table build, bias loads batched under the DMA latency (one wait)
# speedup vs baseline: 1.0007x; 1.0007x over previous
; #define KV_ISSUE(tile_, slot_) do { \
;     const bf16_t* kp_ = kbase + (size_t)(tile_) * 4096 + kvoff; const bf16_t* vp_ = vbase + (size_t)(tile_) * 4096 + kvoff; \
;     char* lp_ = smem + (slot_) * ATT_SLOT + tid * 16; \
;     dma16(kp_, lp_); dma16(kp_ + 2048, lp_ + 4096); dma16(vp_, lp_ + ATT_V); dma16(vp_ + 2048, lp_ + ATT_V + 4096); } while (0)
; template <int KIND>
; DI void attn_unit(const Params& p, int l, int b, int head, int qt, int qcol, int kcol, int vfeat, int gcol, int mixcol,
;                   int t1, int n1, int t2, int n2, char* smem) {
;     ...
;     int nrow = 0, r0w = 0, qc = 0, c0 = 0;
;     if (KIND == 2) {
;         nrow = 2 * qt + (wave >> 1); r0w = min(max(nrow - 4, 0), 24);
;         qc = 32 * (wave & 1) + r; c0 = min(max(qc - 8, 0), 48);
;         float* bias = (float*)(smem + ATT_BIAS);
;         for (int i = tid; i < 15 * 32; i += NTHREADS) { const int rr = i >> 5, cc = i & 31; bias[i] = cc < 31 ? p.rpb[((size_t)l * 6 + head) * 465 + rr * 31 + cc] * LOG2E : -INFINITY; }
;     ...
;     __syncthreads();
;     KV_ISSUE(t1, 0);
;     if (nt > 1) KV_ISSUE((1 < n1) ? t1 + 1 : t2 + (1 - n1), 1);
.LBB0_119:
	s_lshl_b32 s9, s42, 1
	v_sub_u32_e64 v1, s9, 4 clamp
	s_add_i32 s40, s35, 0x180
	v_readfirstlane_b32 s4, v1
	v_sub_u32_e64 v1, s9, 3 clamp
	s_min_u32 s42, s4, 24
	v_readfirstlane_b32 s4, v1
	s_min_u32 s8, s4, 24
	s_add_i32 s4, s35, 0x980
	s_sub_i32 s43, s8, s42
	s_lshr_b32 s4, s4, 6
	s_add_i32 s43, s43, 8
	s_mulk_i32 s4, 0x4800
	s_add_u32 s4, s34, s4
	s_addc_u32 s5, s29, 0
	s_lshl_b64 s[6:7], s[4:5], 7
	s_mul_hi_i32 s4, s50, 12
	s_mul_i32 s50, s50, 12
	s_lshr_b32 s5, s40, 6
	s_add_u32 s5, s50, s5
	s_addc_u32 s4, s4, 0
	s_mul_i32 s4, s4, 0x48000
	s_mul_hi_u32 s40, s5, 0x48000
	s_add_i32 s40, s40, s4
	s_mul_i32 s5, s5, 0x48000
	s_add_u32 s4, s46, s5
	s_addc_u32 s5, s47, s40
	s_load_dwordx2 s[40:41], s[0:1], 0xf8
	s_add_u32 s6, s44, s6
	s_addc_u32 s7, s45, s7
	s_lshl_b64 s[46:47], s[48:49], 2
	v_and_b32_e32 v0, 63, v4
	s_waitcnt lgkmcnt(0)
	s_add_u32 s40, s40, s46
	s_addc_u32 s41, s41, s47
	v_and_b32_e32 v7, 1, v6
	global_load_dword v5, v193, s[40:41] offset:40
	v_lshlrev_b32_e32 v1, 9, v6
	v_lshlrev_b32_e32 v6, 3, v0
	s_movk_i32 s40, 0x1c0
	v_and_or_b32 v1, v6, s40, v1
	v_and_b32_e32 v6, 7, v4
	v_lshlrev_b32_e32 v8, 2, v7
	v_lshrrev_b32_e32 v0, 4, v0
	v_bitop3_b32 v0, v8, v6, v0 bitop3:0x36
	v_lshl_or_b32 v0, v0, 3, v1
	s_lshl_b32 s46, s42, 13
	s_add_u32 s40, s6, s46
	v_ashrrev_i32_e32 v1, 31, v0
	s_addc_u32 s41, s7, 0
	v_lshlrev_b64 v[0:1], 1, v[0:1]
	v_lshl_add_u64 v[8:9], s[40:41], 0, v[0:1]
	s_add_u32 s40, s4, s46
	s_addc_u32 s41, s5, 0
	v_lshl_add_u32 v165, v4, 4, 32
	v_lshl_add_u64 v[10:11], s[40:41], 0, v[0:1]
	v_readfirstlane_b32 s40, v165
	v_add_u32_e32 v6, 0x1000, v165
	s_mov_b32 m0, s40
	v_readfirstlane_b32 s40, v6
	v_add_u32_e32 v6, 0x2000, v165
	s_barrier
	global_load_lds_dwordx4 v[8:9], off
	v_lshl_add_u64 v[8:9], v[8:9], 0, s[26:27]
	s_mov_b32 m0, s40
	v_readfirstlane_b32 s40, v6
	v_add_u32_e32 v6, 0x3000, v165
	global_load_lds_dwordx4 v[8:9], off
	s_mov_b32 m0, s40
	v_readfirstlane_b32 s40, v6
	global_load_lds_dwordx4 v[10:11], off
	v_lshl_add_u64 v[8:9], v[10:11], 0, s[26:27]
	s_mov_b32 m0, s40
	s_cmp_gt_i32 s43, -3
	global_load_lds_dwordx4 v[8:9], off
	s_cbranch_scc0 .LBB0_121
	s_or_b32 s40, s42, 1
	s_sub_i32 s41, 33, s43
	s_cmp_gt_i32 s43, 1
	s_cselect_b32 s40, s40, s41
	s_mov_b32 s41, s75
	s_lshl_b64 s[40:41], s[40:41], 13
	s_add_u32 s46, s6, s40
	s_addc_u32 s47, s7, s41
	s_add_u32 s40, s4, s40
	s_addc_u32 s41, s5, s41
	v_add_u32_e32 v6, 0x4000, v165
	v_lshl_add_u64 v[10:11], s[40:41], 0, v[0:1]
	v_readfirstlane_b32 s40, v6
	v_add_u32_e32 v6, 0x5000, v165
	v_lshl_add_u64 v[8:9], s[46:47], 0, v[0:1]
	s_mov_b32 m0, s40
	v_readfirstlane_b32 s40, v6
	v_add_u32_e32 v6, 0x6000, v165
	global_load_lds_dwordx4 v[8:9], off
	v_lshl_add_u64 v[8:9], v[8:9], 0, s[26:27]
	s_mov_b32 m0, s40
	v_readfirstlane_b32 s40, v6
	v_add_u32_e32 v6, 0x7000, v165
	global_load_lds_dwordx4 v[8:9], off
	s_mov_b32 m0, s40
	v_readfirstlane_b32 s40, v6
	global_load_lds_dwordx4 v[10:11], off
	v_lshl_add_u64 v[8:9], v[10:11], 0, s[26:27]
	s_mov_b32 m0, s40
	s_nop 0
	global_load_lds_dwordx4 v[8:9], off
.LBB0_121:
	s_cmp_lt_i32 s43, -3
	v_lshlrev_b32_e32 v164, 2, v2
	s_cbranch_scc1 .LBB0_106
	v_lshl_or_b32 v6, v7, 5, v3
	v_sub_u32_e64 v7, v6, 8 clamp
	v_min_u32_e32 v7, 48, v7
	s_mov_b64 s[62:63], s[6:7]
	s_mov_b64 s[98:99], s[4:5]
	v_mov_b32_e32 v160, v0
	v_add_u32_e32 v161, 0x1000, v0
	v_readfirstlane_b32 s101, v165
	s_lshr_b32 s100, s35, 6
	s_mul_i32 s41, s60, 6
	s_add_i32 s100, s100, s41
	s_mulk_i32 s100, 0x744
	s_load_dwordx2 s[40:41], s[0:1], 0xa0
	v_and_b32_e32 v236, 31, v200
	v_lshrrev_b32_e32 v237, 5, v200
	v_mul_u32_u24_e32 v237, 31, v237
	v_add_lshl_u32 v237, v237, v236, 2
	v_mov_b32_e32 v238, 0xff800000
	v_mov_b32_e32 v239, 0xff800000
	s_waitcnt lgkmcnt(0)
	s_add_u32 s40, s40, s100
	s_addc_u32 s41, s41, 0
	s_mov_b32 s100, 0xc020
	v_lshl_add_u32 v240, v200, 2, s100
	v_cmp_ne_u32_e32 vcc, 31, v236
	s_and_b64 exec, exec, vcc
	global_load_dword v238, v237, s[40:41]
	v_cmp_gt_u32_e32 vcc, 0xe0, v200
	s_and_b64 exec, exec, vcc
	global_load_dword v239, v237, s[40:41] offset:992
	s_mov_b64 exec, -1
	s_waitcnt vmcnt(0)
	v_mul_f32_e32 v238, 0x3fb8aa3b, v238
	v_mul_f32_e32 v239, 0x3fb8aa3b, v239
	ds_write_b32 v240, v238
	v_cmp_gt_u32_e32 vcc, 0xe0, v200
	s_and_b64 exec, exec, vcc
	ds_write_b32 v240, v239 offset:1024
	s_mov_b64 exec, -1
	s_waitcnt lgkmcnt(0)
	v_sub_u32_e32 v0, v164, v7
	v_sub_u32_e32 v1, v164, v6
	v_lshl_add_u32 v1, v1, 2, 60
	v_cmp_gt_u32_e32 vcc, 16, v0
	v_or_b32_e32 v0, 1, v164
	s_waitcnt vmcnt(0)
; DI int crow(int reg, int h) { return (reg & 3) + 8 * (reg >> 2) + 4 * h; }
; template <int KIND>
; DI void attn_unit(const Params& p, int l, int b, int head, int qt, int qcol, int kcol, int vfeat, int gcol, int mixcol,
;                   int t1, int n1, int t2, int n2, char* smem) {
;     ...
;     if (KIND == 2) {
; #pragma unroll
;         for (int t = 0; t < 2; ++t)
; #pragma unroll
;             for (int e = 0; e < 16; ++e) {
;                 const int kc = 32 * t + crow(e, h);
;                 bcol[t][e] = ((unsigned)(kc - c0) < 16u) ? (kc - qc + 15) * 4 : 31 * 4;
;             }
;     }
;     f32x16 O0[2], O1[2];
; #pragma unroll
;     for (int t = 0; t < 2; ++t)
; #pragma unroll
;         for (int e = 0; e < 16; ++e) { O0[t][e] = 0.f; O1[t][e] = 0.f; }
;     float l0 = 0.f, l1 = 0.f;
;     const float zb = p.lam[8 + l * 4 + ((KIND == 1 && qcol >= 2048) ? 3 : KIND)];
;     f32x16 cz;
; #pragma unroll
;     for (int e = 0; e < 16; ++e) cz[e] = -zb;
	v_xor_b32_e32 v32, 0x80000000, v5
	v_cndmask_b32_e32 v166, v204, v1, vcc
	v_sub_u32_e32 v1, v0, v7
	v_sub_u32_e32 v0, v0, v6
	v_lshl_add_u32 v0, v0, 2, 60
	v_cmp_gt_u32_e32 vcc, 16, v1
	v_mov_b32_e32 v179, 0
	s_mov_b32 s46, 2
	v_cndmask_b32_e32 v167, v204, v0, vcc
	v_or_b32_e32 v0, 2, v164
	v_sub_u32_e32 v1, v0, v7
	v_sub_u32_e32 v0, v0, v6
	v_lshl_add_u32 v0, v0, 2, 60
	v_cmp_gt_u32_e32 vcc, 16, v1
	v_mov_b32_e32 v33, v32
	v_mov_b32_e32 v34, v32
	v_cndmask_b32_e32 v168, v204, v0, vcc
	v_or_b32_e32 v0, 3, v164
	v_sub_u32_e32 v1, v0, v7
	v_sub_u32_e32 v0, v0, v6
	v_lshl_add_u32 v0, v0, 2, 60
	v_cmp_gt_u32_e32 vcc, 16, v1
	v_mov_b32_e32 v35, v32
	v_mov_b32_e32 v36, v32
	v_cndmask_b32_e32 v169, v204, v0, vcc
	v_or_b32_e32 v0, 8, v164
	v_sub_u32_e32 v1, v0, v7
	v_sub_u32_e32 v0, v0, v6
	v_lshl_add_u32 v0, v0, 2, 60
	v_cmp_gt_u32_e32 vcc, 16, v1
	v_mov_b32_e32 v37, v32
	v_mov_b32_e32 v38, v32
	v_cndmask_b32_e32 v170, v204, v0, vcc
	v_or_b32_e32 v0, 9, v164
	v_sub_u32_e32 v1, v0, v7
	v_sub_u32_e32 v0, v0, v6
	v_lshl_add_u32 v0, v0, 2, 60
	v_cmp_gt_u32_e32 vcc, 16, v1
	v_mov_b32_e32 v39, v32
	v_mov_b32_e32 v40, v32
	v_cndmask_b32_e32 v171, v204, v0, vcc
	v_or_b32_e32 v0, 10, v164
	v_sub_u32_e32 v1, v0, v7
	v_sub_u32_e32 v0, v0, v6
	v_lshl_add_u32 v0, v0, 2, 60
	v_cmp_gt_u32_e32 vcc, 16, v1
	v_mov_b32_e32 v41, v32
	v_mov_b32_e32 v42, v32
	v_cndmask_b32_e32 v172, v204, v0, vcc
	v_or_b32_e32 v0, 11, v164
	v_sub_u32_e32 v1, v0, v7
	v_sub_u32_e32 v0, v0, v6
	v_lshl_add_u32 v0, v0, 2, 60
	v_cmp_gt_u32_e32 vcc, 16, v1
	v_mov_b32_e32 v43, v32
	v_mov_b32_e32 v44, v32
	v_cndmask_b32_e32 v173, v204, v0, vcc
	v_or_b32_e32 v0, 16, v164
	v_sub_u32_e32 v1, v0, v7
	v_sub_u32_e32 v0, v0, v6
	v_lshl_add_u32 v0, v0, 2, 60
	v_cmp_gt_u32_e32 vcc, 16, v1
	v_mov_b32_e32 v45, v32
	v_mov_b32_e32 v46, v32
	v_cndmask_b32_e32 v174, v204, v0, vcc
	v_or_b32_e32 v0, 17, v164
	v_sub_u32_e32 v1, v0, v7
	v_sub_u32_e32 v0, v0, v6
	v_lshl_add_u32 v0, v0, 2, 60
	v_cmp_gt_u32_e32 vcc, 16, v1
	v_mov_b32_e32 v47, v32
	s_add_i32 s47, s43, 4
	v_cndmask_b32_e32 v175, v204, v0, vcc
	v_or_b32_e32 v0, 18, v164
	v_sub_u32_e32 v1, v0, v7
	v_sub_u32_e32 v0, v0, v6
	v_lshl_add_u32 v0, v0, 2, 60
	v_cmp_gt_u32_e32 vcc, 16, v1
	v_lshlrev_b32_e32 v217, 7, v3
	s_sub_i32 s50, s42, s8
	v_cndmask_b32_e32 v176, v204, v0, vcc
	v_or_b32_e32 v0, 19, v164
	v_sub_u32_e32 v1, v0, v7
	v_sub_u32_e32 v0, v0, v6
	v_lshl_add_u32 v0, v0, 2, 60
	v_cmp_gt_u32_e32 vcc, 16, v1
	s_mov_b32 s51, 0
	s_mov_b32 s53, 0
	v_cndmask_b32_e32 v177, v204, v0, vcc
	v_or_b32_e32 v0, 24, v164
	v_sub_u32_e32 v1, v0, v7
	v_sub_u32_e32 v0, v0, v6
	v_lshl_add_u32 v0, v0, 2, 60
	v_cmp_gt_u32_e32 vcc, 16, v1
	v_mov_b32_e32 v3, v179
	v_mov_b32_e32 v5, v179
	v_cndmask_b32_e32 v178, v204, v0, vcc
	v_or_b32_e32 v0, 25, v164
	v_sub_u32_e32 v1, v0, v7
	v_sub_u32_e32 v0, v0, v6
	v_lshl_add_u32 v0, v0, 2, 60
	v_cmp_gt_u32_e32 vcc, 16, v1
	v_mov_b32_e32 v8, v179
	v_mov_b32_e32 v9, v179
	v_cndmask_b32_e32 v180, v204, v0, vcc
	v_or_b32_e32 v0, 26, v164
	v_sub_u32_e32 v1, v0, v7
	v_sub_u32_e32 v0, v0, v6
	v_lshl_add_u32 v0, v0, 2, 60
	v_cmp_gt_u32_e32 vcc, 16, v1
	v_mov_b32_e32 v10, v179
	v_mov_b32_e32 v11, v179
	v_cndmask_b32_e32 v181, v204, v0, vcc
	v_or_b32_e32 v0, 27, v164
	v_sub_u32_e32 v1, v0, v7
	v_sub_u32_e32 v0, v0, v6
	v_lshl_add_u32 v0, v0, 2, 60
	v_cmp_gt_u32_e32 vcc, 16, v1
	v_mov_b32_e32 v12, v179
	v_mov_b32_e32 v13, v179
	v_cndmask_b32_e32 v182, v204, v0, vcc
	v_or_b32_e32 v0, 32, v164
	v_sub_u32_e32 v1, v0, v7
	v_sub_u32_e32 v0, v0, v6
	v_lshl_add_u32 v0, v0, 2, 60
	v_cmp_gt_u32_e32 vcc, 16, v1
	v_mov_b32_e32 v14, v179
	v_mov_b32_e32 v15, v179
	v_cndmask_b32_e32 v183, v204, v0, vcc
	v_or_b32_e32 v0, 33, v164
	v_sub_u32_e32 v1, v0, v7
	v_sub_u32_e32 v0, v0, v6
	v_lshl_add_u32 v0, v0, 2, 60
; DI int crow(int reg, int h) { return (reg & 3) + 8 * (reg >> 2) + 4 * h; }
; #define KV_ISSUE(tile_, slot_) do { \
;     const bf16_t* kp_ = kbase + (size_t)(tile_) * 4096 + kvoff; const bf16_t* vp_ = vbase + (size_t)(tile_) * 4096 + kvoff; \
;     char* lp_ = smem + (slot_) * ATT_SLOT + tid * 16; \
;     dma16(kp_, lp_); dma16(kp_ + 2048, lp_ + 4096); dma16(vp_, lp_ + ATT_V); dma16(vp_ + 2048, lp_ + ATT_V + 4096); } while (0)
; template <int KIND>
; DI void attn_unit(const Params& p, int l, int b, int head, int qt, int qcol, int kcol, int vfeat, int gcol, int mixcol,
;                   int t1, int n1, int t2, int n2, char* smem) {
;     ...
;     if (KIND == 2) {
; #pragma unroll
;         for (int t = 0; t < 2; ++t)
; #pragma unroll
;             for (int e = 0; e < 16; ++e) {
;                 const int kc = 32 * t + crow(e, h);
;                 bcol[t][e] = ((unsigned)(kc - c0) < 16u) ? (kc - qc + 15) * 4 : 31 * 4;
;             }
;     }
;     f32x16 O0[2], O1[2];
; #pragma unroll
;     for (int t = 0; t < 2; ++t)
; #pragma unroll
;         for (int e = 0; e < 16; ++e) { O0[t][e] = 0.f; O1[t][e] = 0.f; }
;     float l0 = 0.f, l1 = 0.f;
;     const float zb = p.lam[8 + l * 4 + ((KIND == 1 && qcol >= 2048) ? 3 : KIND)];
;     f32x16 cz;
; #pragma unroll
;     for (int e = 0; e < 16; ++e) cz[e] = -zb;
;     const int kvoff = (8 * wave + (lane >> 3)) * 64 + (((lane & 7) ^ (((wave & 1) << 2) | (lane >> 4))) << 3);
;     const int xr = (r >> 1) & 7;
;     __syncthreads();
;     KV_ISSUE(t1, 0);
;     if (nt > 1) KV_ISSUE((1 < n1) ? t1 + 1 : t2 + (1 - n1), 1);
;     int sc = 0, sn = 2;
;     for (int it = 0; it < nt; ++it) {
;         const int tile = (it < n1) ? t1 + it : t2 + (it - n1);
;         if (it + 1 < nt) asm volatile("s_waitcnt vmcnt(4)" ::: "memory"); else asm volatile("s_waitcnt vmcnt(0)" ::: "memory");
;         __builtin_amdgcn_s_barrier();
;         const char* sk = smem + sc * ATT_SLOT;
;         const char* sv = sk + ATT_V;
;         bool active = true;
;         if (KIND == 2 && tile < 32) active = (tile >= r0w) && (tile < r0w + 8);
	v_cmp_gt_u32_e32 vcc, 16, v1
	v_mov_b32_e32 v16, 0
	v_mov_b32_e32 v17, v179
	v_cndmask_b32_e32 v184, v204, v0, vcc
	v_or_b32_e32 v0, 34, v164
	v_sub_u32_e32 v1, v0, v7
	v_sub_u32_e32 v0, v0, v6
	v_lshl_add_u32 v0, v0, 2, 60
	v_cmp_gt_u32_e32 vcc, 16, v1
	v_mov_b32_e32 v18, v179
	v_mov_b32_e32 v19, v179
	v_cndmask_b32_e32 v185, v204, v0, vcc
	v_or_b32_e32 v0, 35, v164
	v_sub_u32_e32 v1, v0, v7
	v_sub_u32_e32 v0, v0, v6
	v_lshl_add_u32 v0, v0, 2, 60
	v_cmp_gt_u32_e32 vcc, 16, v1
	v_mov_b32_e32 v20, v179
	v_mov_b32_e32 v21, v179
	v_cndmask_b32_e32 v186, v204, v0, vcc
	v_or_b32_e32 v0, 40, v164
	v_sub_u32_e32 v1, v0, v7
	v_sub_u32_e32 v0, v0, v6
	v_lshl_add_u32 v0, v0, 2, 60
	v_cmp_gt_u32_e32 vcc, 16, v1
	v_mov_b32_e32 v22, v179
	v_mov_b32_e32 v23, v179
	v_cndmask_b32_e32 v187, v204, v0, vcc
	v_or_b32_e32 v0, 41, v164
	v_sub_u32_e32 v1, v0, v7
	v_sub_u32_e32 v0, v0, v6
	v_lshl_add_u32 v0, v0, 2, 60
	v_cmp_gt_u32_e32 vcc, 16, v1
	v_mov_b32_e32 v24, v179
	v_mov_b32_e32 v25, v179
	v_cndmask_b32_e32 v188, v204, v0, vcc
	v_or_b32_e32 v0, 42, v164
	v_sub_u32_e32 v1, v0, v7
	v_sub_u32_e32 v0, v0, v6
	v_lshl_add_u32 v0, v0, 2, 60
	v_cmp_gt_u32_e32 vcc, 16, v1
	v_mov_b32_e32 v26, v179
	v_mov_b32_e32 v27, v179
	v_cndmask_b32_e32 v189, v204, v0, vcc
	v_or_b32_e32 v0, 43, v164
	v_sub_u32_e32 v1, v0, v7
	v_sub_u32_e32 v0, v0, v6
	v_lshl_add_u32 v0, v0, 2, 60
	v_cmp_gt_u32_e32 vcc, 16, v1
	v_mov_b32_e32 v28, v179
	v_mov_b32_e32 v29, v179
	v_cndmask_b32_e32 v190, v204, v0, vcc
	v_or_b32_e32 v0, 48, v164
	v_sub_u32_e32 v1, v0, v7
	v_sub_u32_e32 v0, v0, v6
	v_lshl_add_u32 v0, v0, 2, 60
	v_cmp_gt_u32_e32 vcc, 16, v1
	v_mov_b32_e32 v30, v179
	v_mov_b32_e32 v31, v179
	v_cndmask_b32_e32 v191, v204, v0, vcc
	v_or_b32_e32 v0, 49, v164
	v_sub_u32_e32 v1, v0, v7
	v_sub_u32_e32 v0, v0, v6
	v_lshl_add_u32 v0, v0, 2, 60
	v_cmp_gt_u32_e32 vcc, 16, v1
	s_nop 1
	v_cndmask_b32_e32 v192, v204, v0, vcc
	v_or_b32_e32 v0, 50, v164
	v_sub_u32_e32 v1, v0, v7
	v_sub_u32_e32 v0, v0, v6
	v_lshl_add_u32 v0, v0, 2, 60
	v_cmp_gt_u32_e32 vcc, 16, v1
	s_nop 1
	v_cndmask_b32_e32 v194, v204, v0, vcc
	v_or_b32_e32 v0, 51, v164
	v_sub_u32_e32 v1, v0, v7
	v_sub_u32_e32 v0, v0, v6
	v_lshl_add_u32 v0, v0, 2, 60
	v_cmp_gt_u32_e32 vcc, 16, v1
	s_nop 1
	v_cndmask_b32_e32 v195, v204, v0, vcc
	v_or_b32_e32 v0, 56, v164
	v_sub_u32_e32 v1, v0, v7
	v_sub_u32_e32 v0, v0, v6
	v_lshl_add_u32 v0, v0, 2, 60
	v_cmp_gt_u32_e32 vcc, 16, v1
	s_nop 1
	v_cndmask_b32_e32 v196, v204, v0, vcc
	v_or_b32_e32 v0, 57, v164
	v_sub_u32_e32 v1, v0, v7
	v_sub_u32_e32 v0, v0, v6
	v_lshl_add_u32 v0, v0, 2, 60
	v_cmp_gt_u32_e32 vcc, 16, v1
	s_nop 1
	v_cndmask_b32_e32 v197, v204, v0, vcc
	v_or_b32_e32 v0, 58, v164
	v_sub_u32_e32 v1, v0, v7
	v_sub_u32_e32 v0, v0, v6
	v_lshl_add_u32 v0, v0, 2, 60
	v_cmp_gt_u32_e32 vcc, 16, v1
	s_nop 1
	v_cndmask_b32_e32 v198, v204, v0, vcc
	v_or_b32_e32 v0, 59, v164
	v_sub_u32_e32 v1, v0, v7
	v_sub_u32_e32 v0, v0, v6
	v_lshl_add_u32 v0, v0, 2, 60
	v_cmp_gt_u32_e32 vcc, 16, v1
	v_bfe_u32 v1, v4, 1, 3
	v_mov_b32_e32 v6, v179
	v_cndmask_b32_e32 v199, v204, v0, vcc
	v_lshrrev_b32_e32 v0, 1, v4
	v_ashrrev_i32_e32 v4, 7, v4
	v_add_u32_e32 v214, s9, v4
	v_bitop3_b32 v0, v2, v0, 7 bitop3:0x78
	v_max_i32_e32 v4, 4, v214
	v_lshlrev_b32_e32 v218, 4, v0
	v_bitop3_b32 v0, v2, v1, 2 bitop3:0x36
	v_add_u32_e32 v4, -4, v4
	v_lshlrev_b32_e32 v219, 4, v0
	v_bitop3_b32 v0, v2, v1, 4 bitop3:0x36
	v_min_u32_e32 v215, 24, v4
	v_lshlrev_b32_e32 v220, 4, v0
	v_bitop3_b32 v0, v2, v1, 6 bitop3:0x36
	v_add_u32_e32 v216, 8, v215
	v_lshlrev_b32_e32 v221, 4, v0
	v_mov_b32_e32 v0, 0
	v_mov_b32_e32 v1, v179
	v_mov_b32_e32 v2, v179
	v_mov_b32_e32 v4, v179
	v_mov_b32_e32 v7, v179
	s_add_i32 s52, s53, 1
	s_cmp_ge_i32 s52, s47
	s_mov_b64 s[4:5], -1
	s_cbranch_scc0 .LBB0_125
	s_branch .LBB0_124
